# v16 + s6 phase rebalance: blocks 0..43 (halo tile) hand their second proj tile to blocks 44..87
# speedup vs baseline: 1.0495x; 1.0068x over previous
.LBB0_57:
	v_mov_b32_e32 v133, v130
	v_mov_b32_e32 v134, v131
	v_cvt_pk_bf16_f32 v118, v118, v119
	v_add3_u32 v134, s11, v132, v134
	s_ashr_i32 s11, s10, 31
	s_lshl_b64 s[10:11], s[10:11], 1
	v_cvt_pk_bf16_f32 v119, v120, v121
	v_cvt_pk_bf16_f32 v120, v114, v115
	v_add_u32_e32 v114, 16, v134
	v_cvt_pk_bf16_f32 v102, v102, v103
	v_cvt_pk_bf16_f32 v103, v104, v105
	v_cvt_pk_bf16_f32 v104, v98, v99
	v_add_u32_e32 v98, 32, v134
	v_cvt_pk_bf16_f32 v86, v86, v87
	v_cvt_pk_bf16_f32 v87, v88, v89
	v_cvt_pk_bf16_f32 v88, v82, v83
	v_add_u32_e32 v82, 48, v134
	v_cvt_pk_bf16_f32 v70, v70, v71
	v_cvt_pk_bf16_f32 v71, v72, v73
	v_cvt_pk_bf16_f32 v72, v66, v67
	v_add_u32_e32 v66, 64, v134
	v_cvt_pk_bf16_f32 v54, v54, v55
	v_cvt_pk_bf16_f32 v55, v56, v57
	v_cvt_pk_bf16_f32 v56, v50, v51
	v_add_u32_e32 v50, 0x50, v134
	v_cvt_pk_bf16_f32 v38, v38, v39
	v_cvt_pk_bf16_f32 v39, v40, v41
	v_cvt_pk_bf16_f32 v40, v34, v35
	v_add_u32_e32 v34, 0x60, v134
	v_cvt_pk_bf16_f32 v22, v22, v23
	v_cvt_pk_bf16_f32 v23, v24, v25
	v_cvt_pk_bf16_f32 v24, v18, v19
	v_add_u32_e32 v18, 0x70, v134
	s_add_u32 s10, s30, s10
	v_lshl_add_u32 v136, v133, 3, v0
	v_ashrrev_i32_e32 v135, 31, v134
	v_ashrrev_i32_e32 v115, 31, v114
	v_ashrrev_i32_e32 v99, 31, v98
	v_ashrrev_i32_e32 v83, 31, v82
	v_ashrrev_i32_e32 v67, 31, v66
	v_ashrrev_i32_e32 v51, 31, v50
	v_ashrrev_i32_e32 v35, 31, v34
	v_ashrrev_i32_e32 v19, 31, v18
	s_addc_u32 s11, s40, s11
	v_lshlrev_b64 v[138:139], 11, v[134:135]
	v_ashrrev_i32_e32 v137, 31, v136
	v_lshlrev_b64 v[114:115], 11, v[114:115]
	v_lshlrev_b64 v[98:99], 11, v[98:99]
	v_lshlrev_b64 v[82:83], 11, v[82:83]
	v_lshlrev_b64 v[66:67], 11, v[66:67]
	v_lshlrev_b64 v[50:51], 11, v[50:51]
	v_lshlrev_b64 v[34:35], 11, v[34:35]
	v_lshlrev_b64 v[18:19], 11, v[18:19]
	v_lshl_add_u64 v[138:139], s[10:11], 0, v[138:139]
	v_cvt_pk_bf16_f32 v126, v126, v127
	v_cvt_pk_bf16_f32 v127, v128, v129
	v_cvt_pk_bf16_f32 v128, v122, v123
	v_lshlrev_b64 v[122:123], 1, v[136:137]
	v_lshl_add_u64 v[114:115], s[10:11], 0, v[114:115]
	v_lshl_add_u64 v[98:99], s[10:11], 0, v[98:99]
	v_lshl_add_u64 v[82:83], s[10:11], 0, v[82:83]
	v_lshl_add_u64 v[66:67], s[10:11], 0, v[66:67]
	v_lshl_add_u64 v[50:51], s[10:11], 0, v[50:51]
	v_lshl_add_u64 v[34:35], s[10:11], 0, v[34:35]
	v_lshl_add_u64 v[18:19], s[10:11], 0, v[18:19]
	s_add_i32 s25, s25, s15
	v_cvt_pk_bf16_f32 v129, v124, v125
	v_lshl_add_u64 v[124:125], v[138:139], 0, v[122:123]
	v_cvt_pk_bf16_f32 v121, v116, v117
	v_cvt_pk_bf16_f32 v110, v110, v111
	v_cvt_pk_bf16_f32 v111, v112, v113
	v_cvt_pk_bf16_f32 v112, v106, v107
	v_cvt_pk_bf16_f32 v113, v108, v109
	v_lshl_add_u64 v[106:107], v[114:115], 0, v[122:123]
	v_cvt_pk_bf16_f32 v105, v100, v101
	v_cvt_pk_bf16_f32 v94, v94, v95
	v_cvt_pk_bf16_f32 v95, v96, v97
	v_cvt_pk_bf16_f32 v96, v90, v91
	v_cvt_pk_bf16_f32 v97, v92, v93
	v_lshl_add_u64 v[90:91], v[98:99], 0, v[122:123]
	v_cvt_pk_bf16_f32 v89, v84, v85
	v_cvt_pk_bf16_f32 v78, v78, v79
	v_cvt_pk_bf16_f32 v79, v80, v81
	v_cvt_pk_bf16_f32 v80, v74, v75
	v_cvt_pk_bf16_f32 v81, v76, v77
	v_lshl_add_u64 v[74:75], v[82:83], 0, v[122:123]
	v_cvt_pk_bf16_f32 v73, v68, v69
	v_cvt_pk_bf16_f32 v62, v62, v63
	v_cvt_pk_bf16_f32 v63, v64, v65
	v_cvt_pk_bf16_f32 v64, v58, v59
	v_cvt_pk_bf16_f32 v65, v60, v61
	v_lshl_add_u64 v[58:59], v[66:67], 0, v[122:123]
	v_cvt_pk_bf16_f32 v57, v52, v53
	v_cvt_pk_bf16_f32 v46, v46, v47
	v_cvt_pk_bf16_f32 v47, v48, v49
	v_cvt_pk_bf16_f32 v48, v42, v43
	v_cvt_pk_bf16_f32 v49, v44, v45
	v_lshl_add_u64 v[42:43], v[50:51], 0, v[122:123]
	v_cvt_pk_bf16_f32 v41, v36, v37
	v_cvt_pk_bf16_f32 v30, v30, v31
	v_cvt_pk_bf16_f32 v31, v32, v33
	v_cvt_pk_bf16_f32 v32, v26, v27
	v_cvt_pk_bf16_f32 v33, v28, v29
	v_lshl_add_u64 v[26:27], v[34:35], 0, v[122:123]
	v_cvt_pk_bf16_f32 v25, v20, v21
	v_cvt_pk_bf16_f32 v14, v14, v15
	v_cvt_pk_bf16_f32 v15, v16, v17
	v_cvt_pk_bf16_f32 v16, v10, v11
	v_cvt_pk_bf16_f32 v17, v12, v13
	v_lshl_add_u64 v[10:11], v[18:19], 0, v[122:123]
	v_cvt_pk_bf16_f32 v6, v6, v7
	v_cvt_pk_bf16_f32 v7, v8, v9
	v_cvt_pk_bf16_f32 v8, v2, v3
	v_cvt_pk_bf16_f32 v9, v4, v5
	s_cmpk_lg_u32 s100, 0x100
	s_cbranch_scc1 .Lproj_plain
	s_cmpk_gt_i32 s25, 0x1ff
	s_cbranch_scc1 .Lproj_third
	s_cmp_lt_i32 s14, 44
	s_branch .Lproj_tail_done
.Lproj_third:
	s_cmpk_gt_i32 s25, 0x2d3
	s_cbranch_scc1 .Lproj_tail_done
	s_add_i32 s10, s14, 0xffffffd4
	s_cmp_gt_u32 s10, 43
	s_cbranch_scc1 .Lproj_tail_done
	s_add_i32 s25, s25, 0xffffff2c
	s_cmp_eq_u32 s25, -1
	s_branch .Lproj_tail_done
.Lproj_plain:
	s_cmpk_gt_i32 s25, 0x1ff
.Lproj_tail_done:
	global_store_dwordx4 v[124:125], v[126:129], off
	global_store_dwordx4 v[124:125], v[118:121], off offset:64
	global_store_dwordx4 v[106:107], v[110:113], off
	global_store_dwordx4 v[106:107], v[102:105], off offset:64
	global_store_dwordx4 v[90:91], v[94:97], off
	global_store_dwordx4 v[90:91], v[86:89], off offset:64
	global_store_dwordx4 v[74:75], v[78:81], off
	global_store_dwordx4 v[74:75], v[70:73], off offset:64
	global_store_dwordx4 v[58:59], v[62:65], off
	global_store_dwordx4 v[58:59], v[54:57], off offset:64
	global_store_dwordx4 v[42:43], v[46:49], off
	global_store_dwordx4 v[42:43], v[38:41], off offset:64
	global_store_dwordx4 v[26:27], v[30:33], off
	global_store_dwordx4 v[26:27], v[22:25], off offset:64
	global_store_dwordx4 v[10:11], v[14:17], off
	global_store_dwordx4 v[10:11], v[6:9], off offset:64
	s_cbranch_scc1 .LBB0_64
